# norm loops: row parameters requested with the row; helper phase: pure helper workgroups convert FFN weights before waiting for the s5 GEMMs, 5-item waves moved to them
# speedup vs baseline: 1.4372x; 1.0162x over previous
; __device__ __forceinline__ u32x2 pk4(f32x4 v) { u32x2 r; r.x = pk2(v[0], v[1]); r.y = pk2(v[2], v[3]); return r; }
; __device__ __forceinline__ void phase_norm(const PP& p, int l, int which, const float* xsrc, const float* csrc, int share) {
;     ...
;     for (int r = gw; r < MROWS; r += nw) {
;         const int b = r / TT, j = r - b * TT;
;         const float* src = j < CTX ? csrc + ((size_t)b * CTX + j) * DM : xsrc + ((size_t)b * SEQ + (j - CTX)) * DM;
;         const float* mv = mod + (size_t)(j < CTX ? 4 : b) * 6144 + (which == 0 ? 0 : 3072);
;         f32x4 v[4]; float ss = 0.f;
; #pragma unroll
;         for (int i = 0; i < 4; ++i) { v[i] = *(const f32x4*)(src + i * 256 + lane * 4); ss += v[i][0] * v[i][0] + v[i][1] * v[i][1] + v[i][2] * v[i][2] + v[i][3] * v[i][3]; }
;         ss = red64(ss);
;         const float rs = __builtin_amdgcn_rsqf(ss * (1.f / 1024.f) + 1e-6f);
; #pragma unroll
;         for (int i = 0; i < 4; ++i) {
;             const int c = i * 256 + lane * 4;
;             const f32x4 gv = *(const f32x4*)(gain + c), sh = *(const f32x4*)(mv + c), sc = *(const f32x4*)(mv + 1024 + c);
;             const f32x4 y = v[i] * rs * gv * (sc + 1.f) + sh;
;             *(u32x2*)(H + (size_t)r * DM + c) = pk4(y);
;         }
;     }
.LBB0_119:
	s_or_b64 exec, exec, s[24:25]
	v_mov_b32_e32 v7, v0
	v_lshl_add_u64 v[28:29], v[18:19], 0, v[6:7]
	global_load_dwordx4 v[16:19], v[28:29], off
	global_load_dwordx4 v[20:23], v[28:29], off offset:1024
	global_load_dwordx4 v[24:27], v[28:29], off offset:2048
	s_nop 0
	global_load_dwordx4 v[28:31], v[28:29], off offset:3072
	v_lshl_add_u64 v[14:15], v[14:15], 2, s[4:5]
	s_mov_b64 s[6:7], 0x1000
	v_lshl_add_u64 v[120:121], v[14:15], 0, s[6:7]
	v_lshl_add_u64 v[122:123], v[14:15], 0, v[6:7]
	v_lshl_add_u64 v[120:121], v[120:121], 0, v[6:7]
	global_load_dwordx4 v[54:57], v[2:3], off
	global_load_dwordx4 v[58:61], v[2:3], off offset:1024
	global_load_dwordx4 v[62:65], v[2:3], off offset:2048
	global_load_dwordx4 v[66:69], v[2:3], off offset:3072
	global_load_dwordx4 v[70:73], v[120:121], off
	global_load_dwordx4 v[74:77], v[120:121], off offset:1024
	global_load_dwordx4 v[78:81], v[120:121], off offset:2048
	global_load_dwordx4 v[82:85], v[120:121], off offset:3072
	global_load_dwordx4 v[86:89], v[122:123], off
	global_load_dwordx4 v[90:93], v[122:123], off offset:1024
	global_load_dwordx4 v[94:97], v[122:123], off offset:2048
	global_load_dwordx4 v[98:101], v[122:123], off offset:3072
	v_mov_b32_e32 v11, v0
	v_mov_b32_e32 v13, v0
	v_readlane_b32 s6, v254, 7
	v_readlane_b32 s7, v254, 8
	s_waitcnt vmcnt(15)
	v_mul_f32_e32 v7, v17, v17
	s_waitcnt vmcnt(14)
	v_mul_f32_e32 v9, v21, v21
	s_waitcnt vmcnt(13)
	v_mov_b32_e32 v48, v25
	s_waitcnt vmcnt(12)
	v_mov_b32_e32 v49, v29
	v_mov_b32_e32 v14, v24
	v_mov_b32_e32 v15, v28
	v_fmac_f32_e32 v7, v16, v16
	v_fmac_f32_e32 v9, v20, v20
	v_pk_mul_f32 v[48:49], v[48:49], v[48:49]
	v_mov_b32_e32 v50, v26
	v_mov_b32_e32 v51, v30
	v_fmac_f32_e32 v7, v18, v18
	v_fmac_f32_e32 v9, v22, v22
	v_pk_fma_f32 v[14:15], v[14:15], v[14:15], v[48:49]
	v_mov_b32_e32 v52, v27
	v_mov_b32_e32 v53, v31
	v_fmac_f32_e32 v7, v19, v19
	v_fmac_f32_e32 v9, v23, v23
	v_pk_fma_f32 v[14:15], v[50:51], v[50:51], v[14:15]
	v_add_f32_e32 v7, v7, v9
	v_pk_fma_f32 v[14:15], v[52:53], v[52:53], v[14:15]
	v_add_f32_e32 v7, v7, v14
	v_add_f32_e32 v7, v7, v15
	ds_bpermute_b32 v9, v164, v7
	v_add_u32_e32 v1, s6, v1
	s_mov_b32 s6, 0x83ff
	v_cmp_lt_i32_e32 vcc, s6, v1
	s_waitcnt lgkmcnt(0)
	v_add_f32_e32 v7, v7, v9
	ds_bpermute_b32 v9, v165, v7
	v_readlane_b32 s6, v254, 9
	v_readlane_b32 s7, v254, 10
	s_or_b64 s[22:23], vcc, s[22:23]
	s_waitcnt lgkmcnt(0)
	v_add_f32_e32 v7, v7, v9
	ds_bpermute_b32 v9, v166, v7
	s_waitcnt lgkmcnt(0)
	v_add_f32_e32 v7, v7, v9
	ds_bpermute_b32 v9, v167, v7
	s_waitcnt lgkmcnt(0)
	v_add_f32_e32 v7, v7, v9
	ds_bpermute_b32 v9, v168, v7
	s_waitcnt lgkmcnt(0)
	v_add_f32_e32 v7, v7, v9
	ds_bpermute_b32 v9, v169, v7
	s_waitcnt lgkmcnt(0)
	v_add_f32_e32 v7, v7, v9
	v_fmamk_f32 v7, v7, 0x3a800000, v171
	v_rsq_f32_e32 v48, v7
	s_waitcnt vmcnt(0)
	v_pk_mul_f32 v[16:17], v[16:17], v[48:49] op_sel_hi:[1,0]
	v_pk_mul_f32 v[18:19], v[18:19], v[48:49] op_sel_hi:[1,0]
	v_pk_mul_f32 v[16:17], v[54:55], v[16:17]
	v_pk_mul_f32 v[18:19], v[56:57], v[18:19]
	v_pk_add_f32 v[70:71], v[70:71], 1.0 op_sel_hi:[1,0]
	v_pk_add_f32 v[72:73], v[72:73], 1.0 op_sel_hi:[1,0]
	v_pk_fma_f32 v[16:17], v[70:71], v[16:17], v[86:87]
	v_pk_fma_f32 v[18:19], v[72:73], v[18:19], v[88:89]
	v_cvt_pk_bf16_f32 v16, v16, v17
	v_cvt_pk_bf16_f32 v17, v18, v19
	global_store_dwordx2 v[4:5], v[16:17], off offset:-1024
	v_pk_mul_f32 v[20:21], v[20:21], v[48:49] op_sel_hi:[1,0]
	v_pk_mul_f32 v[22:23], v[22:23], v[48:49] op_sel_hi:[1,0]
	v_pk_mul_f32 v[20:21], v[58:59], v[20:21]
	v_pk_mul_f32 v[22:23], v[60:61], v[22:23]
	v_pk_add_f32 v[74:75], v[74:75], 1.0 op_sel_hi:[1,0]
	v_pk_add_f32 v[76:77], v[76:77], 1.0 op_sel_hi:[1,0]
	v_pk_fma_f32 v[20:21], v[74:75], v[20:21], v[90:91]
	v_pk_fma_f32 v[22:23], v[76:77], v[22:23], v[92:93]
	v_cvt_pk_bf16_f32 v20, v20, v21
	v_cvt_pk_bf16_f32 v21, v22, v23
	global_store_dwordx2 v[4:5], v[20:21], off offset:-512
	v_pk_mul_f32 v[24:25], v[24:25], v[48:49] op_sel_hi:[1,0]
	v_pk_mul_f32 v[26:27], v[26:27], v[48:49] op_sel_hi:[1,0]
	v_pk_mul_f32 v[24:25], v[62:63], v[24:25]
	v_pk_mul_f32 v[26:27], v[64:65], v[26:27]
	v_pk_add_f32 v[78:79], v[78:79], 1.0 op_sel_hi:[1,0]
	v_pk_add_f32 v[80:81], v[80:81], 1.0 op_sel_hi:[1,0]
	v_pk_fma_f32 v[24:25], v[78:79], v[24:25], v[94:95]
	v_pk_fma_f32 v[26:27], v[80:81], v[26:27], v[96:97]
	v_cvt_pk_bf16_f32 v24, v24, v25
	v_cvt_pk_bf16_f32 v25, v26, v27
	global_store_dwordx2 v[4:5], v[24:25], off offset:0
	v_pk_mul_f32 v[28:29], v[28:29], v[48:49] op_sel_hi:[1,0]
	v_pk_mul_f32 v[30:31], v[30:31], v[48:49] op_sel_hi:[1,0]
	v_pk_mul_f32 v[28:29], v[66:67], v[28:29]
	v_pk_mul_f32 v[30:31], v[68:69], v[30:31]
	v_pk_add_f32 v[82:83], v[82:83], 1.0 op_sel_hi:[1,0]
	v_pk_add_f32 v[84:85], v[84:85], 1.0 op_sel_hi:[1,0]
	v_pk_fma_f32 v[28:29], v[82:83], v[28:29], v[98:99]
	v_pk_fma_f32 v[30:31], v[84:85], v[30:31], v[100:101]
	v_cvt_pk_bf16_f32 v28, v28, v29
	v_cvt_pk_bf16_f32 v29, v30, v31
	global_store_dwordx2 v[4:5], v[28:29], off offset:512
	v_lshl_add_u64 v[4:5], v[4:5], 0, s[6:7]
	s_andn2_b64 exec, exec, s[22:23]
	s_cbranch_execz .LBB0_124

; __device__ __forceinline__ int tid_of(int wv) { int t = wv * 64 + lane_id(); asm volatile("" : "+v"(t)); return t; }
; __device__ __forceinline__ int bidx() { int t = blockIdx.x; asm volatile("" : "+s"(t)); return t; }
; __global__ void __launch_bounds__(512) fwd_mega(P kp) {
;     ...
;         const bool s5_helpers = nblk >= 224;
;         const int hb0 = s5_helpers ? 192 : 0;
;         if (bidx() >= hb0) {
;             const int tid = tid_of(p.wv);
;             if (tid == 0) {
;                 while (__hip_atomic_load((unsigned*)(p.ws + OFF_BAR) + 3600 + l, __ATOMIC_RELAXED, __HIP_MEMORY_SCOPE_AGENT) < 32u) __builtin_amdgcn_s_sleep(8);
;                 __builtin_amdgcn_fence(__ATOMIC_ACQUIRE, "agent");
;                 asm volatile("s_waitcnt vmcnt(0)" ::: "memory");
;             }
;             __syncthreads();
;             phase_s5post(p, l, (bidx() - hb0) * 8 + (tid >> 6), (nblk - hb0) * 8);
;             phase_gaterw(p, l, (bidx() - hb0) * 8 + (tid >> 6), (nblk - hb0) * 8);
;             __syncthreads();
;             phase_convw(p, l, sm, hb0, nblk - hb0, 1);
;         }
.LBB0_877:
	v_readlane_b32 s0, v252, 0
	v_readlane_b32 s1, v254, 3
	s_cmp_ge_i32 s0, s1
	s_cbranch_scc0 .LBB0_955
	s_mov_b32 s99, 0
	s_cmpk_lt_i32 s0, 0xe0
	s_cbranch_scc1 .Lhelp_main
	s_mov_b32 s99, 1
	s_branch .Lhelp_convw
.Lhelp_main:
	v_mov_b32_e32 v1, v162
	s_nop 0
	v_cmp_eq_u32_e32 vcc, 0, v1
	s_and_saveexec_b64 s[0:1], vcc
	s_cbranch_execz .LBB0_882
	v_readlane_b32 s4, v254, 58
	v_readlane_b32 s5, v254, 59
	s_lshl_b64 s[4:5], s[4:5], 2
	v_readlane_b32 s6, v253, 36
	s_add_u32 s4, s6, s4
	v_readlane_b32 s6, v253, 37
	s_addc_u32 s5, s6, s5
	global_load_dword v2, v0, s[4:5] sc1
	s_waitcnt vmcnt(0)
	v_cmp_lt_u32_e32 vcc, 31, v2
	s_cbranch_vccnz .LBB0_881

; __device__ __forceinline__ int lane_id() { return (int)__builtin_amdgcn_mbcnt_hi(~0u, __builtin_amdgcn_mbcnt_lo(~0u, 0u)); }
; __device__ __forceinline__ int bidx() { int t = blockIdx.x; asm volatile("" : "+s"(t)); return t; }
; __device__ __forceinline__ int s5pos(int j) { if (j < CTX) return j; const int tok = j - CTX; return CTX + (tok & 63) * 128 + (tok >> 6); }
; __device__ __forceinline__ void phase_s5post(const PP& p, int l, int gw, int nw) {
;     int lane = lane_id(); asm volatile("" : "+v"(lane));
;     const int fr = lane & 15, fq = lane >> 4;
;     const bf16_t* A2 = (const bf16_t*)(p.ws + OFF_A2); const bf16_t* Y5 = (const bf16_t*)(p.ws + OFF_Y5); bf16_t* Y5w = (bf16_t*)(p.ws + OFF_Y5);
;     const bf16_t* GLU = (const bf16_t*)(p.ws + OFF_GLU);
;     for (int item = gw; item < MROWS / 16; item += nw) {
;         const int row = item * 16 + fr, b = row / TT, j = row - b * TT;
;         {
;             const int n = s5pos(j), R = b * NCH + (n >> 5), t = n & 31;
;             const size_t GS5 = (size_t)GROWS * 512;
;             bf16x8 yf[8];
; #pragma unroll
;             for (int ks = 0; ks < 8; ++ks) {
;                 const int ch = ks * 32 + fq * 8, g = ch >> 4, hh = ch & 15;
;                 const u32x4 y0 = *(const u32x4*)(Y5 + (size_t)(g * 2) * GS5 + (size_t)R * 512 + t * 16 + hh), y1 = *(const u32x4*)(Y5 + (size_t)(g * 2 + 1) * GS5 + (size_t)R * 512 + t * 16 + hh);
; __global__ void __launch_bounds__(512) fwd_mega(P kp) {
;     ...
;             phase_s5post(p, l, (bidx() - hb0) * 8 + (tid >> 6), (nblk - hb0) * 8);
;             phase_gaterw(p, l, (bidx() - hb0) * 8 + (tid >> 6), (nblk - hb0) * 8);
.LBB0_882:
	s_or_b64 exec, exec, s[0:1]
	v_readlane_b32 s0, v252, 0
	s_barrier
	v_readlane_b32 s1, v254, 3
	s_sub_i32 s0, s0, s1
	v_ashrrev_i32_e32 v1, 6, v1
	v_lshl_add_u32 v101, s0, 3, v1
	v_readlane_b32 s0, v253, 47
	s_add_i32 s0, s0, -1
	v_sub_u32_e32 v101, s0, v101
	s_movk_i32 s0, 0x840
	v_mov_b32_e32 v2, v163
	v_cmp_gt_i32_e32 vcc, s0, v101
	s_and_saveexec_b64 s[0:1], vcc
	s_cbranch_execz .LBB0_887
	v_ashrrev_i32_e32 v5, 4, v2
	v_and_b32_e32 v120, 15, v2
	v_lshlrev_b32_e32 v2, 3, v5
	v_and_b32_e32 v4, 8, v2
	v_readlane_b32 s4, v253, 30
	v_lshlrev_b32_e32 v6, 1, v4
	v_mov_b32_e32 v7, v0
	v_readlane_b32 s5, v253, 31
	s_mov_b32 s6, 0x108000
	v_ashrrev_i32_e32 v3, 31, v2
	v_lshl_add_u64 v[50:51], s[4:5], 0, v[6:7]
	v_readlane_b32 s4, v254, 58
	v_readlane_b32 s5, v254, 59
	v_lshlrev_b32_e32 v6, 2, v5
	v_and_b32_e32 v7, -2, v5
	v_or_b32_e32 v5, 1, v5
	s_lshl_b32 s12, s4, 8
	v_mad_i64_i32 v[54:55], s[4:5], v5, s6, 0
	v_add_u32_e32 v5, 32, v2
	v_ashrrev_i32_e32 v5, 3, v5
	v_mad_i64_i32 v[52:53], s[4:5], v7, s6, 0
	v_mad_i64_i32 v[56:57], s[4:5], v7, s20, 0
	v_and_b32_e32 v7, -2, v5
	v_or_b32_e32 v5, 1, v5
	v_mad_i64_i32 v[60:61], s[4:5], v5, s6, 0
	v_add_u32_e32 v5, 64, v2
	v_ashrrev_i32_e32 v5, 3, v5
	v_mad_i64_i32 v[58:59], s[4:5], v7, s6, 0
	v_mad_i64_i32 v[62:63], s[4:5], v7, s20, 0
	v_and_b32_e32 v7, -2, v5
	v_or_b32_e32 v5, 1, v5
	s_waitcnt vmcnt(3)
	v_mad_i64_i32 v[66:67], s[4:5], v5, s6, 0
	v_add_u32_e32 v5, 0x60, v2
	v_ashrrev_i32_e32 v5, 3, v5
	v_mad_i64_i32 v[64:65], s[4:5], v7, s6, 0
	v_mad_i64_i32 v[68:69], s[4:5], v7, s20, 0
	v_and_b32_e32 v7, -2, v5
	v_or_b32_e32 v5, 1, v5
	s_waitcnt vmcnt(2)
	v_mad_i64_i32 v[72:73], s[4:5], v5, s6, 0
	v_add_u32_e32 v5, 0x80, v2
	v_ashrrev_i32_e32 v5, 3, v5
	v_mad_i64_i32 v[70:71], s[4:5], v7, s6, 0
	s_waitcnt vmcnt(1)
	v_mad_i64_i32 v[74:75], s[4:5], v7, s20, 0
	v_and_b32_e32 v7, -2, v5
	v_or_b32_e32 v5, 1, v5
	s_waitcnt vmcnt(0)
	v_mad_i64_i32 v[78:79], s[4:5], v5, s6, 0
	v_add_u32_e32 v5, 0xa0, v2
	v_ashrrev_i32_e32 v5, 3, v5
	v_mad_i64_i32 v[76:77], s[4:5], v7, s6, 0
	v_mad_i64_i32 v[80:81], s[4:5], v7, s20, 0
	v_and_b32_e32 v7, -2, v5
	v_or_b32_e32 v5, 1, v5
	v_mad_i64_i32 v[84:85], s[4:5], v5, s6, 0
	v_add_u32_e32 v5, 0xc0, v2
	v_ashrrev_i32_e32 v5, 3, v5
	v_mad_i64_i32 v[82:83], s[4:5], v7, s6, 0
	v_mad_i64_i32 v[86:87], s[4:5], v7, s20, 0
	v_and_b32_e32 v7, -2, v5
	v_or_b32_e32 v5, 1, v5
	v_mad_i64_i32 v[90:91], s[4:5], v5, s6, 0
	v_add_u32_e32 v5, 0xe0, v2
	v_ashrrev_i32_e32 v5, 3, v5
	v_mad_i64_i32 v[88:89], s[4:5], v7, s6, 0
	v_mad_i64_i32 v[92:93], s[4:5], v7, s20, 0
	v_and_b32_e32 v7, -2, v5
	v_or_b32_e32 v5, 1, v5
	v_mad_i64_i32 v[94:95], s[4:5], v7, s6, 0
	v_mad_i64_i32 v[96:97], s[4:5], v5, s6, 0
	v_mad_i64_i32 v[98:99], s[4:5], v7, s20, 0
	v_readlane_b32 s4, v254, 53
	v_and_b32_e32 v100, 24, v2
	v_lshlrev_b32_e32 v8, 9, v120
	v_mov_b32_e32 v9, v0
	v_ashrrev_i32_e32 v7, 31, v6
	v_readlane_b32 s5, v254, 54
	v_or_b32_e32 v102, 0x19bbc000, v100
	v_mov_b32_e32 v103, v0
	v_lshl_add_u64 v[104:105], v[2:3], 1, v[8:9]
	v_lshl_add_u64 v[106:107], v[6:7], 2, s[4:5]
	s_mov_b64 s[34:35], 0
	v_lshlrev_b32_e32 v108, 1, v4
	s_lshl_b64 s[36:37], s[12:13], 2
	v_lshlrev_b64 v[110:111], 2, v[2:3]

; __device__ __forceinline__ int lane_id() { return (int)__builtin_amdgcn_mbcnt_hi(~0u, __builtin_amdgcn_mbcnt_lo(~0u, 0u)); }
; __device__ __forceinline__ int bidx() { int t = blockIdx.x; asm volatile("" : "+s"(t)); return t; }
; __device__ __forceinline__ void phase_gaterw(const PP& p, int l, int gw, int nw) {
;     int lane = lane_id(); asm volatile("" : "+v"(lane));
;     const int fr = lane & 15, fq = lane >> 4;
;     const bf16_t* Z = (const bf16_t*)(p.ws + OFF_Z); const bf16_t* GUP = (const bf16_t*)(p.ws + OFF_GUP);
;     const float* mu = p.in[I_MU] + l * 1408;
;     for (int item = gw; item < MROWS / 16; item += nw) {
;         const int row = item * 16 + fr, b = row / TT, j = row - b * TT;
;         const bool hp = (j != 0) && (j != CTX), hn = (j != CTX - 1) && (j != TT - 1);
;         bf16x8 gfrag[4];
; #pragma unroll
;         for (int ks = 0; ks < 4; ++ks) {
;             const int c0 = 1280 + ks * 32 + fq * 8;
; __global__ void __launch_bounds__(512) fwd_mega(P kp) {
;     ...
;             phase_gaterw(p, l, (bidx() - hb0) * 8 + (tid >> 6), (nblk - hb0) * 8);
.LBB0_887:
	s_or_b64 exec, exec, s[0:1]
	v_readlane_b32 s1, v254, 17
	v_readlane_b32 s0, v252, 0
	v_mov_b32_e32 v2, v163
	v_mov_b32_e32 v3, s1
	ds_read_b64 v[4:5], v3
	v_readlane_b32 s1, v254, 3
	s_sub_i32 s0, s0, s1
	v_lshl_add_u32 v41, s0, 3, v1
	v_readlane_b32 s0, v253, 47
	s_add_i32 s0, s0, -1
	v_sub_u32_e32 v41, s0, v41
	s_movk_i32 s0, 0x840
	s_waitcnt lgkmcnt(0)
	v_readfirstlane_b32 s4, v5
	v_readfirstlane_b32 s5, v4
	v_cmp_gt_i32_e32 vcc, s0, v41
	s_and_saveexec_b64 s[0:1], vcc
	s_cbranch_execz .LBB0_924
	v_readlane_b32 s6, v254, 62
	v_readlane_b32 s7, v254, 63
	s_lshl_b64 s[6:7], s[6:7], 2
	v_ashrrev_i32_e32 v1, 4, v2
	v_and_b32_e32 v94, 15, v2
	s_add_u32 s6, s5, s6
	v_lshlrev_b32_e32 v2, 3, v1
	s_addc_u32 s7, s4, s7
	v_ashrrev_i32_e32 v3, 31, v2
	v_lshl_add_u64 v[6:7], v[2:3], 2, s[6:7]
	s_mov_b64 s[4:5], 0x1400
	v_lshl_add_u64 v[26:27], v[6:7], 0, s[4:5]
	s_mov_b64 s[4:5], 0x1480
	v_lshl_add_u64 v[28:29], v[6:7], 0, s[4:5]
	s_mov_b64 s[4:5], 0x1500
	v_lshl_add_u64 v[30:31], v[6:7], 0, s[4:5]
	s_mov_b64 s[4:5], 0x1580
	v_lshlrev_b32_e32 v4, 2, v1
	v_lshl_add_u64 v[32:33], v[6:7], 0, s[4:5]
	v_readlane_b32 s4, v253, 28
	v_ashrrev_i32_e32 v5, 31, v4
	v_lshlrev_b64 v[2:3], 1, v[2:3]
	v_readlane_b32 s5, v253, 29
	v_lshlrev_b32_e32 v6, 8, v94
	v_mov_b32_e32 v7, v0
	v_lshl_add_u64 v[34:35], s[4:5], 0, v[2:3]
	v_lshl_add_u64 v[36:37], v[6:7], 0, v[2:3]
	v_lshlrev_b64 v[38:39], 1, v[4:5]
	s_mov_b64 s[4:5], 0

; __device__ __forceinline__ int bidx() { int t = blockIdx.x; asm volatile("" : "+s"(t)); return t; }
; __device__ __forceinline__ void phase_convw(const PP& p, int l, float* sm, int w0, int nwb, int ffn) {
;     constexpr int T0 = 832, T1 = T0 + 256, T2 = T1 + 1408, T3 = T2 + 704, T4 = T3 + 12, T5 = T4 + 12, T6 = T5 + 12, T7 = T6 + 16;
;     const int wb = bidx() - w0;
;     if (wb < 0 || wb >= nwb) return;
;     const int nt = ffn ? (T3 - T1) : (T7 - (T3 - T1));
;     for (int tt = wb; tt < nt; tt += nwb) {
;         const int t = ffn ? tt + T1 : (tt < T1 ? tt : tt + (T3 - T1));
; __global__ void __launch_bounds__(512) fwd_mega(P kp) {
;     ...
;             __syncthreads();
;             phase_convw(p, l, sm, hb0, nblk - hb0, 1);
.LBB0_924:
	s_or_b64 exec, exec, s[0:1]
	s_cmp_eq_u32 s99, 2
	s_cbranch_scc1 .LBB0_955
.Lhelp_convw:
	v_readlane_b32 s12, v252, 0
	v_readlane_b32 s0, v254, 3
	s_barrier
	s_sub_i32 s6, s12, s0
	s_cmp_gt_i32 s6, -1
	v_readlane_b32 s4, v253, 46
	s_cselect_b64 s[0:1], -1, 0
	s_cmp_lt_i32 s6, s4
	s_cselect_b64 s[4:5], -1, 0
	s_and_b64 s[0:1], s[0:1], s[4:5]
	s_cmpk_lt_u32 s6, 0x840
	s_cselect_b64 s[4:5], -1, 0
	s_and_b64 s[0:1], s[0:1], s[4:5]
	s_andn2_b64 vcc, exec, s[0:1]
	s_cbranch_vccnz .Lhelp_after_convw
	v_readlane_b32 s4, v254, 58
	s_lshl_b32 s7, s12, 6
	v_readlane_b32 s22, v254, 0
	v_readlane_b32 s5, v254, 59
	s_add_i32 s7, s22, s7
	s_lshl_b32 s12, s12, 2
	v_readlane_b32 s22, v254, 5
	s_mul_hi_u32 s1, s4, 0xb00000
	s_mul_i32 s0, s4, 0xb00000
	s_lshl_b64 s[4:5], s[4:5], 22
	s_add_i32 s24, s22, s12
	s_branch .LBB0_928

; __device__ __forceinline__ int tid_of(int wv) { int t = wv * 64 + lane_id(); asm volatile("" : "+v"(t)); return t; }
; __device__ __forceinline__ int bidx() { int t = blockIdx.x; asm volatile("" : "+s"(t)); return t; }
; __global__ void __launch_bounds__(512) fwd_mega(P kp) {
;     ...
;         const bool s5_helpers = nblk >= 224;
;         const int hb0 = s5_helpers ? 192 : 0;
;         if (bidx() >= hb0) {
;             const int tid = tid_of(p.wv);
;             if (tid == 0) {
;                 while (__hip_atomic_load((unsigned*)(p.ws + OFF_BAR) + 3600 + l, __ATOMIC_RELAXED, __HIP_MEMORY_SCOPE_AGENT) < 32u) __builtin_amdgcn_s_sleep(8);
;                 __builtin_amdgcn_fence(__ATOMIC_ACQUIRE, "agent");
;                 asm volatile("s_waitcnt vmcnt(0)" ::: "memory");
;             }
;             __syncthreads();
;             phase_s5post(p, l, (bidx() - hb0) * 8 + (tid >> 6), (nblk - hb0) * 8);
;             phase_gaterw(p, l, (bidx() - hb0) * 8 + (tid >> 6), (nblk - hb0) * 8);
;             __syncthreads();
;             phase_convw(p, l, sm, hb0, nblk - hb0, 1);
;         }
.Lhelp_after_convw:
	s_cmp_eq_u32 s99, 1
	s_cbranch_scc0 .LBB0_955
	s_mov_b32 s99, 2
	s_mov_b64 exec, -1
	s_branch .Lhelp_main

; __device__ __forceinline__ u32x2 pk4(f32x4 v) { u32x2 r; r.x = pk2(v[0], v[1]); r.y = pk2(v[2], v[3]); return r; }
; __device__ __forceinline__ void phase_norm(const PP& p, int l, int which, const float* xsrc, const float* csrc, int share) {
;     ...
;     for (int r = gw; r < MROWS; r += nw) {
;         const int b = r / TT, j = r - b * TT;
;         const float* src = j < CTX ? csrc + ((size_t)b * CTX + j) * DM : xsrc + ((size_t)b * SEQ + (j - CTX)) * DM;
;         const float* mv = mod + (size_t)(j < CTX ? 4 : b) * 6144 + (which == 0 ? 0 : 3072);
;         f32x4 v[4]; float ss = 0.f;
; #pragma unroll
;         for (int i = 0; i < 4; ++i) { v[i] = *(const f32x4*)(src + i * 256 + lane * 4); ss += v[i][0] * v[i][0] + v[i][1] * v[i][1] + v[i][2] * v[i][2] + v[i][3] * v[i][3]; }
;         ss = red64(ss);
;         const float rs = __builtin_amdgcn_rsqf(ss * (1.f / 1024.f) + 1e-6f);
; #pragma unroll
;         for (int i = 0; i < 4; ++i) {
;             const int c = i * 256 + lane * 4;
;             const f32x4 gv = *(const f32x4*)(gain + c), sh = *(const f32x4*)(mv + c), sc = *(const f32x4*)(mv + 1024 + c);
;             const f32x4 y = v[i] * rs * gv * (sc + 1.f) + sh;
;             *(u32x2*)(H + (size_t)r * DM + c) = pk4(y);
;         }
;     }
.LBB0_1154:
	s_or_b64 exec, exec, s[24:25]
	v_mov_b32_e32 v27, v0
	v_lshl_add_u64 v[2:3], v[4:5], 0, v[26:27]
	global_load_dwordx4 v[16:19], v[2:3], off
	global_load_dwordx4 v[10:13], v[2:3], off offset:1024
	global_load_dwordx4 v[108:111], v[2:3], off offset:2048
	global_load_dwordx4 v[104:107], v[2:3], off offset:3072
	v_lshl_add_u64 v[14:15], v[14:15], 2, s[4:5]
	s_mov_b64 s[24:25], 0x1000
	v_lshl_add_u64 v[120:121], v[14:15], 0, s[24:25]
	v_lshl_add_u64 v[122:123], v[14:15], 0, v[26:27]
	v_lshl_add_u64 v[120:121], v[120:121], 0, v[26:27]
	global_load_dwordx4 v[54:57], v[22:23], off
	global_load_dwordx4 v[58:61], v[22:23], off offset:1024
	global_load_dwordx4 v[62:65], v[22:23], off offset:2048
	global_load_dwordx4 v[66:69], v[22:23], off offset:3072
	global_load_dwordx4 v[70:73], v[120:121], off
	global_load_dwordx4 v[74:77], v[120:121], off offset:1024
	global_load_dwordx4 v[78:81], v[120:121], off offset:2048
	global_load_dwordx4 v[82:85], v[120:121], off offset:3072
	global_load_dwordx4 v[86:89], v[122:123], off
	global_load_dwordx4 v[90:93], v[122:123], off offset:1024
	global_load_dwordx4 v[94:97], v[122:123], off offset:2048
	global_load_dwordx4 v[98:101], v[122:123], off offset:3072
	v_readlane_b32 s24, v254, 7
	v_readlane_b32 s25, v254, 8
	s_mov_b32 s12, 0x83ff
	v_add_u32_e32 v1, s24, v1
	v_readlane_b32 s24, v254, 9
	v_readlane_b32 s25, v254, 10
	v_cmp_lt_i32_e32 vcc, s12, v1
	s_or_b64 s[22:23], vcc, s[22:23]
	s_waitcnt vmcnt(15)
	v_mul_f32_e32 v4, v17, v17
	s_waitcnt vmcnt(14)
	v_mul_f32_e32 v5, v11, v11
	v_fmac_f32_e32 v4, v16, v16
	v_fmac_f32_e32 v5, v10, v10
	v_fmac_f32_e32 v4, v18, v18
	v_fmac_f32_e32 v5, v12, v12
	v_fmac_f32_e32 v4, v19, v19
	v_fmac_f32_e32 v5, v13, v13
	v_add_f32_e32 v29, v4, v5
	s_waitcnt vmcnt(12)
	v_mov_b32_e32 v34, v109
	v_mov_b32_e32 v35, v105
	v_mov_b32_e32 v20, v108
	v_mov_b32_e32 v21, v104
	v_pk_mul_f32 v[34:35], v[34:35], v[34:35]
	s_nop 0
	v_pk_fma_f32 v[20:21], v[20:21], v[20:21], v[34:35]
	v_mov_b32_e32 v34, v110
	v_mov_b32_e32 v35, v106
	v_pk_fma_f32 v[20:21], v[34:35], v[34:35], v[20:21]
	v_mov_b32_e32 v34, v111
	v_mov_b32_e32 v35, v107
	v_pk_fma_f32 v[20:21], v[34:35], v[34:35], v[20:21]
	s_nop 0
	v_add_f32_e32 v20, v29, v20
	v_add_f32_e32 v20, v20, v21
	ds_bpermute_b32 v21, v164, v20
	v_mov_b32_e32 v29, v0
	s_waitcnt lgkmcnt(0)
	v_add_f32_e32 v20, v20, v21
	ds_bpermute_b32 v21, v165, v20
	s_waitcnt lgkmcnt(0)
	v_add_f32_e32 v20, v20, v21
	ds_bpermute_b32 v21, v166, v20
	s_waitcnt lgkmcnt(0)
	v_add_f32_e32 v20, v20, v21
	ds_bpermute_b32 v21, v167, v20
	s_waitcnt lgkmcnt(0)
	v_add_f32_e32 v20, v20, v21
	ds_bpermute_b32 v21, v168, v20
	s_waitcnt lgkmcnt(0)
	v_add_f32_e32 v20, v20, v21
	ds_bpermute_b32 v21, v169, v20
	s_waitcnt lgkmcnt(0)
	v_add_f32_e32 v20, v20, v21
	v_fmamk_f32 v20, v20, 0x3a800000, v171
	v_rsq_f32_e32 v34, v20
	s_waitcnt vmcnt(0)
	v_pk_mul_f32 v[16:17], v[16:17], v[34:35] op_sel_hi:[1,0]
	v_pk_mul_f32 v[18:19], v[18:19], v[34:35] op_sel_hi:[1,0]
	v_pk_mul_f32 v[16:17], v[54:55], v[16:17]
	v_pk_mul_f32 v[18:19], v[56:57], v[18:19]
	v_pk_add_f32 v[70:71], v[70:71], 1.0 op_sel_hi:[1,0]
	v_pk_add_f32 v[72:73], v[72:73], 1.0 op_sel_hi:[1,0]
	v_pk_fma_f32 v[16:17], v[70:71], v[16:17], v[86:87]
	v_pk_fma_f32 v[18:19], v[72:73], v[18:19], v[88:89]
	v_cvt_pk_bf16_f32 v16, v16, v17
	v_cvt_pk_bf16_f32 v17, v18, v19
	global_store_dwordx2 v[24:25], v[16:17], off offset:-1024
	v_pk_mul_f32 v[10:11], v[10:11], v[34:35] op_sel_hi:[1,0]
	v_pk_mul_f32 v[12:13], v[12:13], v[34:35] op_sel_hi:[1,0]
	v_pk_mul_f32 v[10:11], v[58:59], v[10:11]
	v_pk_mul_f32 v[12:13], v[60:61], v[12:13]
	v_pk_add_f32 v[74:75], v[74:75], 1.0 op_sel_hi:[1,0]
	v_pk_add_f32 v[76:77], v[76:77], 1.0 op_sel_hi:[1,0]
	v_pk_fma_f32 v[10:11], v[74:75], v[10:11], v[90:91]
	v_pk_fma_f32 v[12:13], v[76:77], v[12:13], v[92:93]
	v_cvt_pk_bf16_f32 v10, v10, v11
	v_cvt_pk_bf16_f32 v11, v12, v13
	global_store_dwordx2 v[24:25], v[10:11], off offset:-512
	v_pk_mul_f32 v[108:109], v[108:109], v[34:35] op_sel_hi:[1,0]
	v_pk_mul_f32 v[110:111], v[110:111], v[34:35] op_sel_hi:[1,0]
	v_pk_mul_f32 v[108:109], v[62:63], v[108:109]
	v_pk_mul_f32 v[110:111], v[64:65], v[110:111]
	v_pk_add_f32 v[78:79], v[78:79], 1.0 op_sel_hi:[1,0]
	v_pk_add_f32 v[80:81], v[80:81], 1.0 op_sel_hi:[1,0]
	v_pk_fma_f32 v[108:109], v[78:79], v[108:109], v[94:95]
	v_pk_fma_f32 v[110:111], v[80:81], v[110:111], v[96:97]
	v_cvt_pk_bf16_f32 v108, v108, v109
	v_cvt_pk_bf16_f32 v109, v110, v111
	global_store_dwordx2 v[24:25], v[108:109], off offset:0
	v_pk_mul_f32 v[104:105], v[104:105], v[34:35] op_sel_hi:[1,0]
	v_pk_mul_f32 v[106:107], v[106:107], v[34:35] op_sel_hi:[1,0]
	v_pk_mul_f32 v[104:105], v[66:67], v[104:105]
	v_pk_mul_f32 v[106:107], v[68:69], v[106:107]
	v_pk_add_f32 v[82:83], v[82:83], 1.0 op_sel_hi:[1,0]
	v_pk_add_f32 v[84:85], v[84:85], 1.0 op_sel_hi:[1,0]
	v_pk_fma_f32 v[104:105], v[82:83], v[104:105], v[98:99]
	v_pk_fma_f32 v[106:107], v[84:85], v[106:107], v[100:101]
	v_cvt_pk_bf16_f32 v104, v104, v105
	v_cvt_pk_bf16_f32 v105, v106, v107
	global_store_dwordx2 v[24:25], v[104:105], off offset:512
	v_lshl_add_u64 v[24:25], v[24:25], 0, s[24:25]
	s_andn2_b64 exec, exec, s[22:23]
	s_cbranch_execz .LBB0_1159
